# v39 + phase-0 gain-folding copies: the 4 per-row-group gain loads fetched together (one address + immediate offsets), later ones replaced by moves
# baseline (speedup 1.0000x reference)
.LBB0_448:
	s_andn2_b64 vcc, exec, s[12:13]
	s_cbranch_vccnz .LBB0_458
	s_load_dwordx2 s[12:13], s[58:59], 0xa0
	s_load_dwordx2 s[38:39], s[58:59], 0x28
	v_mov_b32_e32 v10, v243
	s_waitcnt lgkmcnt(0)
	s_add_u32 s14, s12, s23
	s_addc_u32 s15, s13, s22
	s_lshl_b64 s[12:13], s[4:5], 2
	s_add_u32 s12, s38, s12
	s_addc_u32 s13, s39, s13
	s_add_i32 s52, s16, 0xff00
	s_and_b32 s17, s52, 0xffff
	s_mul_i32 s17, s17, 0xba2f
	s_lshr_b32 s53, s17, 22
	s_mulk_i32 s53, 0x58
	s_sub_i32 s52, s52, s53
	s_lshr_b32 s17, s17, 16
	s_lshl_b32 s53, s52, 8
	s_and_b32 s17, s17, 0xffc0
	s_and_b32 s53, s53, 0x3ff00
	v_lshlrev_b32_e32 v0, 2, v10
	s_add_u32 s14, s14, s53
	v_and_b32_e32 v0, 60, v0
	s_addc_u32 s15, s15, 0
	v_lshlrev_b32_e32 v0, 2, v0
	v_ashrrev_i32_e32 v11, 4, v10
	v_lshl_add_u64 v[6:7], s[14:15], 0, v[0:1]
	v_add_u32_e32 v8, s17, v11
	v_mad_i64_i32 v[2:3], s[14:15], v8, s74, v[6:7]
	v_mov_b32_e32 v70, s74
	v_lshlrev_b32_e32 v70, 4, v70
	v_mov_b32_e32 v71, 0
	v_lshl_add_u64 v[72:73], v[2:3], 0, v[70:71]
	v_lshl_add_u64 v[74:75], v[72:73], 0, v[70:71]
	v_lshl_add_u64 v[76:77], v[74:75], 0, v[70:71]
	s_barrier
	global_load_dwordx4 v[2:5], v[2:3], off
	global_load_dwordx4 v[80:83], v[72:73], off
	global_load_dwordx4 v[84:87], v[74:75], off
	global_load_dwordx4 v[88:91], v[76:77], off
	s_cmp_lg_u64 s[38:39], 0
	s_cselect_b64 s[14:15], -1, 0
	s_cmp_eq_u64 s[38:39], 0
	s_cbranch_scc1 .LBB0_451
	v_ashrrev_i32_e32 v9, 31, v8
	v_lshl_add_u64 v[8:9], v[8:9], 2, s[12:13]
	global_load_dword v93, v[8:9], off offset:64
	global_load_dword v94, v[8:9], off offset:128
	global_load_dword v95, v[8:9], off offset:192
	global_load_dword v8, v[8:9], off
	s_waitcnt vmcnt(0)
	v_pk_mul_f32 v[4:5], v[4:5], v[8:9] op_sel_hi:[1,0]
	v_pk_mul_f32 v[2:3], v[2:3], v[8:9] op_sel_hi:[1,0]
.LBB0_451:
	v_mul_lo_u32 v8, v11, s77
	v_add_u32_e32 v11, 0x100, v10
	v_add3_u32 v8, s78, v8, v0
	v_ashrrev_i32_e32 v12, 4, v11
	s_waitcnt vmcnt(0)
	ds_write2_b32 v8, v2, v3 offset1:1
	ds_write2_b32 v8, v4, v5 offset0:2 offset1:3
	v_add_u32_e32 v8, s17, v12
	v_mad_i64_i32 v[2:3], s[38:39], v8, s74, v[6:7]
	v_mov_b32_e32 v2, v80
	v_mov_b32_e32 v3, v81
	v_mov_b32_e32 v4, v82
	v_mov_b32_e32 v5, v83
	v_cndmask_b32_e64 v9, 0, 1, s[14:15]
	v_cmp_ne_u32_e64 s[38:39], 1, v9
	s_andn2_b64 vcc, exec, s[14:15]
	s_cbranch_vccnz .LBB0_453
	v_ashrrev_i32_e32 v9, 31, v8
	v_lshl_add_u64 v[8:9], v[8:9], 2, s[12:13]
	v_mov_b32_e32 v8, v93
	s_waitcnt vmcnt(0)
	v_pk_mul_f32 v[4:5], v[4:5], v[8:9] op_sel_hi:[1,0]
	v_pk_mul_f32 v[2:3], v[2:3], v[8:9] op_sel_hi:[1,0]
.LBB0_453:
	v_mul_lo_u32 v8, v12, s77
	v_add3_u32 v8, s78, v8, v0
	s_waitcnt vmcnt(0)
	ds_write2_b32 v8, v2, v3 offset1:1
	ds_write2_b32 v8, v4, v5 offset0:2 offset1:3
	v_add_u32_e32 v2, 0x200, v10
	v_ashrrev_i32_e32 v12, 4, v2
	v_add_u32_e32 v8, s17, v12
	v_mad_i64_i32 v[2:3], s[14:15], v8, s74, v[6:7]
	v_mov_b32_e32 v2, v84
	v_mov_b32_e32 v3, v85
	v_mov_b32_e32 v4, v86
	v_mov_b32_e32 v5, v87
	s_and_b64 vcc, exec, s[38:39]
	s_cbranch_vccnz .LBB0_455
	v_ashrrev_i32_e32 v9, 31, v8
	v_lshl_add_u64 v[8:9], v[8:9], 2, s[12:13]
	v_mov_b32_e32 v8, v94
	s_waitcnt vmcnt(0)
	v_pk_mul_f32 v[4:5], v[4:5], v[8:9] op_sel_hi:[1,0]
	v_pk_mul_f32 v[2:3], v[2:3], v[8:9] op_sel_hi:[1,0]
.LBB0_455:
	v_mul_lo_u32 v8, v12, s77
	v_add3_u32 v8, s78, v8, v0
	s_waitcnt vmcnt(0)
	ds_write2_b32 v8, v2, v3 offset1:1
	ds_write2_b32 v8, v4, v5 offset0:2 offset1:3
	v_add_u32_e32 v2, 0x300, v10
	v_ashrrev_i32_e32 v12, 4, v2
	v_add_u32_e32 v8, s17, v12
	v_mad_i64_i32 v[2:3], s[14:15], v8, s74, v[6:7]
	v_mov_b32_e32 v2, v88
	v_mov_b32_e32 v3, v89
	v_mov_b32_e32 v4, v90
	v_mov_b32_e32 v5, v91
	s_and_b64 vcc, exec, s[38:39]
	s_cbranch_vccnz .LBB0_457
	v_ashrrev_i32_e32 v9, 31, v8
	v_lshl_add_u64 v[6:7], v[8:9], 2, s[12:13]
	v_mov_b32_e32 v6, v95
	s_waitcnt vmcnt(0)
	v_pk_mul_f32 v[4:5], v[4:5], v[6:7] op_sel_hi:[1,0]
	v_pk_mul_f32 v[2:3], v[2:3], v[6:7] op_sel_hi:[1,0]

.LBB0_465:
	s_andn2_b64 vcc, exec, s[12:13]
	s_cbranch_vccnz .LBB0_475
	s_load_dwordx2 s[12:13], s[58:59], 0x78
	s_load_dwordx2 s[38:39], s[58:59], 0x18
	v_mov_b32_e32 v10, v243
	s_waitcnt lgkmcnt(0)
	s_add_u32 s14, s12, s6
	s_addc_u32 s15, s13, s7
	s_lshl_b64 s[12:13], s[4:5], 2
	s_add_u32 s12, s38, s12
	s_addc_u32 s13, s39, s13
	s_and_b32 s0, s42, 0x3c0
	s_and_b32 s16, s45, 0x3c0
	s_lshl_b32 s17, s0, 2
	v_lshlrev_b32_e32 v0, 2, v10
	v_ashrrev_i32_e32 v11, 4, v10
	s_add_u32 s14, s14, s17
	v_and_b32_e32 v0, 60, v0
	v_add_u32_e32 v8, s16, v11
	s_addc_u32 s15, s15, 0
	v_lshlrev_b32_e32 v0, 2, v0
	v_ashrrev_i32_e32 v9, 31, v8
	v_lshl_add_u64 v[6:7], s[14:15], 0, v[0:1]
	v_lshlrev_b64 v[2:3], 12, v[8:9]
	v_lshl_add_u64 v[2:3], v[6:7], 0, v[2:3]
	v_mov_b32_e32 v70, 0x10000
	v_mov_b32_e32 v71, 0
	v_lshl_add_u64 v[72:73], v[2:3], 0, v[70:71]
	v_lshl_add_u64 v[74:75], v[72:73], 0, v[70:71]
	v_lshl_add_u64 v[76:77], v[74:75], 0, v[70:71]
	s_barrier
	global_load_dwordx4 v[2:5], v[2:3], off
	global_load_dwordx4 v[80:83], v[72:73], off
	global_load_dwordx4 v[84:87], v[74:75], off
	global_load_dwordx4 v[88:91], v[76:77], off
	s_cmp_lg_u64 s[38:39], 0
	s_cselect_b64 s[14:15], -1, 0
	s_cmp_eq_u64 s[38:39], 0
	s_cbranch_scc1 .LBB0_468
	v_lshl_add_u64 v[8:9], v[8:9], 2, s[12:13]
	global_load_dword v93, v[8:9], off offset:64
	global_load_dword v94, v[8:9], off offset:128
	global_load_dword v95, v[8:9], off offset:192
	global_load_dword v8, v[8:9], off
	s_waitcnt vmcnt(0)
	v_pk_mul_f32 v[4:5], v[4:5], v[8:9] op_sel_hi:[1,0]
	v_pk_mul_f32 v[2:3], v[2:3], v[8:9] op_sel_hi:[1,0]
.LBB0_468:
	v_mul_lo_u32 v8, v11, s77
	v_add_u32_e32 v11, 0x100, v10
	v_add3_u32 v8, s78, v8, v0
	v_ashrrev_i32_e32 v12, 4, v11
	s_waitcnt vmcnt(0)
	ds_write2_b32 v8, v2, v3 offset1:1
	ds_write2_b32 v8, v4, v5 offset0:2 offset1:3
	v_add_u32_e32 v8, s16, v12
	v_ashrrev_i32_e32 v9, 31, v8
	v_lshlrev_b64 v[2:3], 12, v[8:9]
	v_lshl_add_u64 v[2:3], v[6:7], 0, v[2:3]
	v_mov_b32_e32 v2, v80
	v_mov_b32_e32 v3, v81
	v_mov_b32_e32 v4, v82
	v_mov_b32_e32 v5, v83
	v_cndmask_b32_e64 v13, 0, 1, s[14:15]
	v_cmp_ne_u32_e64 s[38:39], 1, v13
	s_andn2_b64 vcc, exec, s[14:15]
	s_cbranch_vccnz .LBB0_470
	v_lshl_add_u64 v[8:9], v[8:9], 2, s[12:13]
	v_mov_b32_e32 v8, v93
	s_waitcnt vmcnt(0)
	v_pk_mul_f32 v[4:5], v[4:5], v[8:9] op_sel_hi:[1,0]
	v_pk_mul_f32 v[2:3], v[2:3], v[8:9] op_sel_hi:[1,0]
.LBB0_470:
	v_mul_lo_u32 v8, v12, s77
	v_add3_u32 v8, s78, v8, v0
	s_waitcnt vmcnt(0)
	ds_write2_b32 v8, v2, v3 offset1:1
	ds_write2_b32 v8, v4, v5 offset0:2 offset1:3
	v_add_u32_e32 v2, 0x200, v10
	v_ashrrev_i32_e32 v12, 4, v2
	v_add_u32_e32 v8, s16, v12
	v_ashrrev_i32_e32 v9, 31, v8
	v_lshlrev_b64 v[2:3], 12, v[8:9]
	v_lshl_add_u64 v[2:3], v[6:7], 0, v[2:3]
	v_mov_b32_e32 v2, v84
	v_mov_b32_e32 v3, v85
	v_mov_b32_e32 v4, v86
	v_mov_b32_e32 v5, v87
	s_and_b64 vcc, exec, s[38:39]
	s_cbranch_vccnz .LBB0_472
	v_lshl_add_u64 v[8:9], v[8:9], 2, s[12:13]
	v_mov_b32_e32 v8, v94
	s_waitcnt vmcnt(0)
	v_pk_mul_f32 v[4:5], v[4:5], v[8:9] op_sel_hi:[1,0]
	v_pk_mul_f32 v[2:3], v[2:3], v[8:9] op_sel_hi:[1,0]
.LBB0_472:
	v_mul_lo_u32 v8, v12, s77
	v_add3_u32 v8, s78, v8, v0
	s_waitcnt vmcnt(0)
	ds_write2_b32 v8, v2, v3 offset1:1
	ds_write2_b32 v8, v4, v5 offset0:2 offset1:3
	v_add_u32_e32 v2, 0x300, v10
	v_ashrrev_i32_e32 v12, 4, v2
	v_add_u32_e32 v8, s16, v12
	v_ashrrev_i32_e32 v9, 31, v8
	v_lshlrev_b64 v[2:3], 12, v[8:9]
	v_lshl_add_u64 v[2:3], v[6:7], 0, v[2:3]
	v_mov_b32_e32 v2, v88
	v_mov_b32_e32 v3, v89
	v_mov_b32_e32 v4, v90
	v_mov_b32_e32 v5, v91
	s_and_b64 vcc, exec, s[38:39]
	s_cbranch_vccnz .LBB0_474
	v_lshl_add_u64 v[6:7], v[8:9], 2, s[12:13]
	v_mov_b32_e32 v6, v95
	s_waitcnt vmcnt(0)
	v_pk_mul_f32 v[4:5], v[4:5], v[6:7] op_sel_hi:[1,0]
	v_pk_mul_f32 v[2:3], v[2:3], v[6:7] op_sel_hi:[1,0]

.LBB0_479:
	s_andn2_b64 vcc, exec, s[12:13]
	s_cbranch_vccnz .LBB0_440
	s_add_u32 s12, s58, s41
	s_addc_u32 s13, s59, 0
	s_load_dwordx2 s[12:13], s[12:13], 0x0
	s_mul_hi_i32 s0, s11, 0x2aaaaaab
	s_load_dwordx2 s[38:39], s[58:59], 0x10
	v_mov_b32_e32 v10, v243
	s_waitcnt lgkmcnt(0)
	s_add_u32 s52, s12, s37
	s_addc_u32 s53, s13, s36
	s_lshl_b64 s[12:13], s[4:5], 2
	s_add_u32 s14, s38, s12
	s_addc_u32 s15, s39, s13
	s_lshr_b32 s12, s0, 31
	s_ashr_i32 s0, s0, 3
	s_add_i32 s0, s0, s12
	s_mul_i32 s13, s0, 0xfffff400
	s_add_i32 s16, s42, s13
	s_ashr_i32 s17, s16, 31
	s_lshl_b32 s12, s0, 6
	s_lshl_b64 s[16:17], s[16:17], 2
	v_lshlrev_b32_e32 v0, 2, v10
	s_add_u32 s16, s52, s16
	v_and_b32_e32 v0, 60, v0
	s_addc_u32 s17, s53, s17
	v_lshlrev_b32_e32 v0, 2, v0
	v_ashrrev_i32_e32 v11, 4, v10
	v_lshl_add_u64 v[6:7], s[16:17], 0, v[0:1]
	v_add_u32_e32 v8, s12, v11
	v_mad_i64_i32 v[2:3], s[16:17], v8, s76, v[6:7]
	v_mov_b32_e32 v70, s76
	v_lshlrev_b32_e32 v70, 4, v70
	v_mov_b32_e32 v71, 0
	v_lshl_add_u64 v[72:73], v[2:3], 0, v[70:71]
	v_lshl_add_u64 v[74:75], v[72:73], 0, v[70:71]
	v_lshl_add_u64 v[76:77], v[74:75], 0, v[70:71]
	s_barrier
	global_load_dwordx4 v[2:5], v[2:3], off
	global_load_dwordx4 v[80:83], v[72:73], off
	global_load_dwordx4 v[84:87], v[74:75], off
	global_load_dwordx4 v[88:91], v[76:77], off
	s_cmp_lg_u64 s[38:39], 0
	s_cselect_b64 s[16:17], -1, 0
	s_cmp_eq_u64 s[38:39], 0
	s_cbranch_scc1 .LBB0_482
	v_ashrrev_i32_e32 v9, 31, v8
	v_lshl_add_u64 v[8:9], v[8:9], 2, s[14:15]
	global_load_dword v93, v[8:9], off offset:64
	global_load_dword v94, v[8:9], off offset:128
	global_load_dword v95, v[8:9], off offset:192
	global_load_dword v8, v[8:9], off
	s_waitcnt vmcnt(0)
	v_pk_mul_f32 v[4:5], v[4:5], v[8:9] op_sel_hi:[1,0]
	v_pk_mul_f32 v[2:3], v[2:3], v[8:9] op_sel_hi:[1,0]
.LBB0_482:
	v_mul_lo_u32 v8, v11, s77
	v_add_u32_e32 v11, 0x100, v10
	v_add3_u32 v8, s78, v8, v0
	v_ashrrev_i32_e32 v12, 4, v11
	s_waitcnt vmcnt(0)
	ds_write2_b32 v8, v2, v3 offset1:1
	ds_write2_b32 v8, v4, v5 offset0:2 offset1:3
	v_add_u32_e32 v8, s12, v12
	v_mad_i64_i32 v[2:3], s[38:39], v8, s76, v[6:7]
	v_mov_b32_e32 v2, v80
	v_mov_b32_e32 v3, v81
	v_mov_b32_e32 v4, v82
	v_mov_b32_e32 v5, v83
	v_cndmask_b32_e64 v9, 0, 1, s[16:17]
	v_cmp_ne_u32_e64 s[38:39], 1, v9
	s_andn2_b64 vcc, exec, s[16:17]
	s_cbranch_vccnz .LBB0_484
	v_ashrrev_i32_e32 v9, 31, v8
	v_lshl_add_u64 v[8:9], v[8:9], 2, s[14:15]
	v_mov_b32_e32 v8, v93
	s_waitcnt vmcnt(0)
	v_pk_mul_f32 v[4:5], v[4:5], v[8:9] op_sel_hi:[1,0]
	v_pk_mul_f32 v[2:3], v[2:3], v[8:9] op_sel_hi:[1,0]
.LBB0_484:
	v_mul_lo_u32 v8, v12, s77
	v_add3_u32 v8, s78, v8, v0
	s_waitcnt vmcnt(0)
	ds_write2_b32 v8, v2, v3 offset1:1
	ds_write2_b32 v8, v4, v5 offset0:2 offset1:3
	v_add_u32_e32 v2, 0x200, v10
	v_ashrrev_i32_e32 v12, 4, v2
	v_add_u32_e32 v8, s12, v12
	v_mad_i64_i32 v[2:3], s[16:17], v8, s76, v[6:7]
	v_mov_b32_e32 v2, v84
	v_mov_b32_e32 v3, v85
	v_mov_b32_e32 v4, v86
	v_mov_b32_e32 v5, v87
	s_and_b64 vcc, exec, s[38:39]
	s_cbranch_vccnz .LBB0_486
	v_ashrrev_i32_e32 v9, 31, v8
	v_lshl_add_u64 v[8:9], v[8:9], 2, s[14:15]
	v_mov_b32_e32 v8, v94
	s_waitcnt vmcnt(0)
	v_pk_mul_f32 v[4:5], v[4:5], v[8:9] op_sel_hi:[1,0]
	v_pk_mul_f32 v[2:3], v[2:3], v[8:9] op_sel_hi:[1,0]
.LBB0_486:
	v_mul_lo_u32 v8, v12, s77
	v_add3_u32 v8, s78, v8, v0
	s_waitcnt vmcnt(0)
	ds_write2_b32 v8, v2, v3 offset1:1
	ds_write2_b32 v8, v4, v5 offset0:2 offset1:3
	v_add_u32_e32 v2, 0x300, v10
	v_ashrrev_i32_e32 v12, 4, v2
	v_add_u32_e32 v8, s12, v12
	v_mad_i64_i32 v[2:3], s[16:17], v8, s76, v[6:7]
	v_mov_b32_e32 v2, v88
	v_mov_b32_e32 v3, v89
	v_mov_b32_e32 v4, v90
	v_mov_b32_e32 v5, v91
	s_and_b64 vcc, exec, s[38:39]
	s_cbranch_vccnz .LBB0_439
	v_ashrrev_i32_e32 v9, 31, v8
	v_lshl_add_u64 v[6:7], v[8:9], 2, s[14:15]
	v_mov_b32_e32 v6, v95
	s_waitcnt vmcnt(0)
	v_pk_mul_f32 v[4:5], v[4:5], v[6:7] op_sel_hi:[1,0]
	v_pk_mul_f32 v[2:3], v[2:3], v[6:7] op_sel_hi:[1,0]
	s_branch .LBB0_439
